# stack3 + sample top-k radix step (LDS reads batched, DPP wave reduction) + prompt attention softmax reductions on DPP (first query copy)
# speedup vs baseline: 1.0078x; 1.0067x over previous
.LBB0_1745:
	ds_read2st64_b32 v[28:29], v22 offset1:8
	ds_read2st64_b32 v[30:31], v22 offset0:16 offset1:24
	ds_read2st64_b32 v[32:33], v22 offset0:32 offset1:40
	ds_read2st64_b32 v[34:35], v22 offset0:48 offset1:56
	ds_read2st64_b32 v[36:37], v22 offset0:64 offset1:72
	ds_read2st64_b32 v[38:39], v22 offset0:80 offset1:88
	ds_read2st64_b32 v[40:41], v22 offset0:96 offset1:104
	ds_read2st64_b32 v[42:43], v22 offset0:112 offset1:120
	v_add_u32_e32 v5, -8, v5
	s_add_i32 s27, s27, 16
	v_add_u32_e32 v22, 0x8000, v22
	s_waitcnt vmcnt(5)
	s_waitcnt lgkmcnt(4)
	v_cmp_ge_u32_e64 s[36:37], v28, v21
	v_cmp_ge_u32_e64 s[38:39], v29, v21
	v_cmp_ge_u32_e64 s[40:41], v30, v21
	v_cmp_ge_u32_e64 s[42:43], v31, v21
	v_addc_co_u32_e64 v6, s[44:45], 0, v6, s[36:37]
	v_cmp_ge_u32_e64 s[36:37], v32, v21
	v_addc_co_u32_e64 v7, s[44:45], 0, v7, s[38:39]
	v_cmp_ge_u32_e64 s[38:39], v33, v21
	v_addc_co_u32_e64 v6, s[44:45], 0, v6, s[40:41]
	v_cmp_ge_u32_e64 s[40:41], v34, v21
	v_addc_co_u32_e64 v7, s[44:45], 0, v7, s[42:43]
	v_cmp_ge_u32_e64 s[42:43], v35, v21
	s_waitcnt lgkmcnt(0)
	v_addc_co_u32_e64 v6, s[44:45], 0, v6, s[36:37]
	v_cmp_ge_u32_e64 s[36:37], v36, v21
	v_addc_co_u32_e64 v7, s[44:45], 0, v7, s[38:39]
	v_cmp_ge_u32_e64 s[38:39], v37, v21
	v_addc_co_u32_e64 v6, s[44:45], 0, v6, s[40:41]
	v_cmp_ge_u32_e64 s[40:41], v38, v21
	v_addc_co_u32_e64 v7, s[44:45], 0, v7, s[42:43]
	v_cmp_ge_u32_e64 s[42:43], v39, v21
	v_addc_co_u32_e64 v6, s[44:45], 0, v6, s[36:37]
	v_cmp_ge_u32_e64 s[36:37], v40, v21
	v_addc_co_u32_e64 v7, s[44:45], 0, v7, s[38:39]
	v_cmp_ge_u32_e64 s[38:39], v41, v21
	v_addc_co_u32_e64 v6, s[44:45], 0, v6, s[40:41]
	v_cmp_ge_u32_e64 s[40:41], v42, v21
	v_addc_co_u32_e64 v7, s[44:45], 0, v7, s[42:43]
	v_cmp_ge_u32_e64 s[42:43], v43, v21
	v_addc_co_u32_e64 v6, s[44:45], 0, v6, s[36:37]
	v_addc_co_u32_e64 v7, s[44:45], 0, v7, s[38:39]
	v_addc_co_u32_e64 v6, s[44:45], 0, v6, s[40:41]
	v_addc_co_u32_e64 v7, s[44:45], 0, v7, s[42:43]
	v_cmp_eq_u32_e32 vcc, 0, v5
	s_nop 1
	s_or_b64 s[22:23], vcc, s[22:23]
	v_mov_b32_e32 v23, s27
	s_andn2_b64 exec, exec, s[22:23]
	s_cbranch_execnz .LBB0_1745
	s_or_b64 exec, exec, s[22:23]

.LBB0_1759:
	s_or_b64 exec, exec, s[16:17]
	s_nop 1
	v_add_f32_dpp v5, v5, v5 quad_perm:[1,0,3,2] row_mask:0xf bank_mask:0xf bound_ctrl:1
	s_nop 1
	v_add_f32_dpp v5, v5, v5 quad_perm:[2,3,0,1] row_mask:0xf bank_mask:0xf bound_ctrl:1
	s_nop 1
	v_add_f32_dpp v5, v5, v5 row_half_mirror row_mask:0xf bank_mask:0xf bound_ctrl:1
	s_nop 1
	v_add_f32_dpp v5, v5, v5 row_mirror row_mask:0xf bank_mask:0xf bound_ctrl:1
	s_nop 1
	v_add_f32_dpp v5, v5, v5 row_bcast:15 row_mask:0xa bank_mask:0xf
	s_nop 1
	v_add_f32_dpp v5, v5, v5 row_bcast:31 row_mask:0xc bank_mask:0xf
	s_nop 1
	v_readlane_b32 s36, v5, 63
	s_and_saveexec_b64 s[14:15], s[0:1]
	s_cbranch_execz .LBB0_1740
	v_mov_b32_e32 v5, s36
	v_cvt_i32_f32_e32 v5, v5
	ds_write_b32 v13, v5
	s_branch .LBB0_1740

.LBB0_2595:
	v_cmp_gt_u32_e64 s[18:19], s40, v146
	v_mov_b32_e32 v102, 0xff61b1e6
	v_lshl_add_u32 v98, v146, 4, v138
	v_mov_b32_e32 v104, 0xff61b1e6
	s_and_saveexec_b64 s[0:1], s[18:19]
	ds_read_b32 v104, v98 offset:1024
	s_or_b64 exec, exec, s[0:1]
	v_or_b32_e32 v99, 64, v146
	v_cmp_gt_u32_e64 s[20:21], s40, v99
	v_lshl_add_u32 v99, v99, 4, v138
	s_and_saveexec_b64 s[0:1], s[20:21]
	ds_read_b32 v102, v99 offset:1024
	s_or_b64 exec, exec, s[0:1]
	v_or_b32_e32 v100, 0x80, v146
	v_cmp_gt_u32_e64 s[22:23], s40, v100
	v_mov_b32_e32 v103, 0xff61b1e6
	v_lshl_add_u32 v100, v100, 4, v138
	v_mov_b32_e32 v105, 0xff61b1e6
	s_and_saveexec_b64 s[0:1], s[22:23]
	ds_read_b32 v105, v100 offset:1024
	s_or_b64 exec, exec, s[0:1]
	v_or_b32_e32 v101, 0xc0, v146
	v_cmp_gt_u32_e64 s[24:25], s40, v101
	v_lshl_add_u32 v101, v101, 4, v138
	s_and_saveexec_b64 s[0:1], s[24:25]
	ds_read_b32 v103, v101 offset:1024
	s_or_b64 exec, exec, s[0:1]
	v_and_b32_e32 v141, 64, v182
	v_add_u32_e32 v106, 64, v141
	v_xor_b32_e32 v107, 32, v182
	v_cmp_lt_i32_e32 vcc, v107, v106
	s_waitcnt lgkmcnt(0)
	v_max_f32_e32 v108, v105, v105
	v_cndmask_b32_e32 v107, v182, v107, vcc
	v_lshlrev_b32_e32 v132, 2, v107
	v_xor_b32_e32 v107, 16, v182
	v_cmp_lt_i32_e32 vcc, v107, v106
	s_nop 1
	v_cndmask_b32_e32 v107, v182, v107, vcc
	v_lshlrev_b32_e32 v133, 2, v107
	v_xor_b32_e32 v107, 8, v182
	v_cmp_lt_i32_e32 vcc, v107, v106
	s_nop 1
	v_cndmask_b32_e32 v107, v182, v107, vcc
	v_lshlrev_b32_e32 v136, 2, v107
	v_xor_b32_e32 v107, 4, v182
	v_cmp_lt_i32_e32 vcc, v107, v106
	s_nop 1
	v_cndmask_b32_e32 v107, v182, v107, vcc
	v_lshlrev_b32_e32 v137, 2, v107
	v_xor_b32_e32 v107, 2, v182
	v_cmp_lt_i32_e32 vcc, v107, v106
	s_nop 1
	v_cndmask_b32_e32 v107, v182, v107, vcc
	v_lshlrev_b32_e32 v139, 2, v107
	v_xor_b32_e32 v107, 1, v182
	v_cmp_lt_i32_e32 vcc, v107, v106
	s_nop 1
	v_cndmask_b32_e32 v106, v182, v107, vcc
	v_max_f32_e32 v107, v103, v103
	v_max_f32_e32 v107, v108, v107
	v_max3_f32 v107, v104, v102, v107
	v_lshlrev_b32_e32 v140, 2, v106
	v_lshlrev_b32_e32 v106, 1, v146
	s_waitcnt lgkmcnt(0)
	s_nop 1
	v_max_f32_dpp v107, v107, v107 quad_perm:[1,0,3,2] row_mask:0xf bank_mask:0xf bound_ctrl:1
	s_nop 1
	v_max_f32_dpp v107, v107, v107 quad_perm:[2,3,0,1] row_mask:0xf bank_mask:0xf bound_ctrl:1
	s_nop 1
	v_max_f32_dpp v107, v107, v107 row_half_mirror row_mask:0xf bank_mask:0xf bound_ctrl:1
	s_nop 1
	v_max_f32_dpp v107, v107, v107 row_mirror row_mask:0xf bank_mask:0xf bound_ctrl:1
	s_nop 1
	v_max_f32_dpp v107, v107, v107 row_bcast:15 row_mask:0xa bank_mask:0xf
	s_nop 1
	v_max_f32_dpp v107, v107, v107 row_bcast:31 row_mask:0xc bank_mask:0xf
	s_nop 1
	v_readlane_b32 s32, v107, 63
	s_nop 3
	v_mov_b32_e32 v107, s32
	v_sub_f32_e32 v104, v104, v107
	v_mul_f32_e32 v104, 0x3fb8aa3b, v104
	v_sub_f32_e32 v102, v102, v107
	v_exp_f32_e32 v104, v104
	v_mul_f32_e32 v102, 0x3fb8aa3b, v102
	v_sub_f32_e32 v105, v105, v107
	v_exp_f32_e32 v102, v102
	v_mul_f32_e32 v105, 0x3fb8aa3b, v105
	v_sub_f32_e32 v103, v103, v107
	v_exp_f32_e32 v105, v105
	v_mul_f32_e32 v103, 0x3fb8aa3b, v103
	v_exp_f32_e32 v103, v103
	v_cndmask_b32_e64 v104, 0, v104, s[18:19]
	v_add_f32_e32 v108, 0, v104
	v_cndmask_b32_e64 v109, 0, v102, s[20:21]
	v_add_f32_e32 v102, v109, v108
	v_cndmask_b32_e64 v105, 0, v105, s[22:23]
	v_add_f32_e32 v102, v105, v102
	v_cndmask_b32_e64 v103, 0, v103, s[24:25]
	v_add_f32_e32 v102, v103, v102
	s_waitcnt lgkmcnt(0)
	s_nop 1
	v_add_f32_dpp v102, v102, v102 quad_perm:[1,0,3,2] row_mask:0xf bank_mask:0xf bound_ctrl:1
	s_nop 1
	v_add_f32_dpp v102, v102, v102 quad_perm:[2,3,0,1] row_mask:0xf bank_mask:0xf bound_ctrl:1
	s_nop 1
	v_add_f32_dpp v102, v102, v102 row_half_mirror row_mask:0xf bank_mask:0xf bound_ctrl:1
	s_nop 1
	v_add_f32_dpp v102, v102, v102 row_mirror row_mask:0xf bank_mask:0xf bound_ctrl:1
	s_nop 1
	v_add_f32_dpp v102, v102, v102 row_bcast:15 row_mask:0xa bank_mask:0xf
	s_nop 1
	v_add_f32_dpp v102, v102, v102 row_bcast:31 row_mask:0xc bank_mask:0xf
	s_nop 1
	v_readlane_b32 s32, v102, 63
	s_nop 3
	v_mov_b32_e32 v102, s32
	v_div_scale_f32 v107, s[0:1], v102, v102, 1.0
	v_rcp_f32_e32 v108, v107
	s_nop 0
	v_fma_f32 v110, -v107, v108, 1.0
	v_fmac_f32_e32 v108, v110, v108
	v_div_scale_f32 v110, vcc, 1.0, v102, 1.0
	v_mul_f32_e32 v111, v110, v108
	v_fma_f32 v112, -v107, v111, v110
	v_fmac_f32_e32 v111, v112, v108
	v_fma_f32 v107, -v107, v111, v110
	v_div_fmas_f32 v107, v107, v108, v111
	v_div_fixup_f32 v107, v107, v102, 1.0
	v_mul_f32_e32 v102, v104, v107
	v_cvt_pk_bf16_f32 v104, v102, s0
	v_add_u32_e32 v102, v138, v106
	ds_write_b16 v102, v104 offset:5120
	v_mul_f32_e32 v104, v109, v107
	v_cvt_pk_bf16_f32 v104, v104, s0
	v_mul_f32_e32 v103, v103, v107
	ds_write_b16 v102, v104 offset:5248
	v_mul_f32_e32 v104, v105, v107
	v_cvt_pk_bf16_f32 v103, v103, s0
	v_cvt_pk_bf16_f32 v104, v104, s0
	ds_write_b16 v102, v103 offset:5504
	v_mov_b32_e32 v103, 0xff61b1e6
	v_mov_b32_e32 v106, 0xff61b1e6
	ds_write_b16 v102, v104 offset:5376
	s_and_saveexec_b64 s[0:1], s[18:19]
	ds_read_b32 v106, v98 offset:1028
	s_or_b64 exec, exec, s[0:1]
	s_and_saveexec_b64 s[0:1], s[20:21]
	ds_read_b32 v103, v99 offset:1028
	s_or_b64 exec, exec, s[0:1]
	v_mov_b32_e32 v104, 0xff61b1e6
	v_mov_b32_e32 v105, 0xff61b1e6
	s_and_saveexec_b64 s[0:1], s[22:23]
	ds_read_b32 v105, v100 offset:1028
	s_or_b64 exec, exec, s[0:1]
	s_and_saveexec_b64 s[0:1], s[24:25]
	ds_read_b32 v104, v101 offset:1028
	s_or_b64 exec, exec, s[0:1]
	s_waitcnt lgkmcnt(0)
	v_max_f32_e32 v107, v104, v104
	v_max_f32_e32 v108, v105, v105
	v_max_f32_e32 v107, v108, v107
	v_max3_f32 v107, v106, v103, v107
	s_waitcnt lgkmcnt(0)
	s_nop 1
	v_max_f32_dpp v107, v107, v107 quad_perm:[1,0,3,2] row_mask:0xf bank_mask:0xf bound_ctrl:1
	s_nop 1
	v_max_f32_dpp v107, v107, v107 quad_perm:[2,3,0,1] row_mask:0xf bank_mask:0xf bound_ctrl:1
	s_nop 1
	v_max_f32_dpp v107, v107, v107 row_half_mirror row_mask:0xf bank_mask:0xf bound_ctrl:1
	s_nop 1
	v_max_f32_dpp v107, v107, v107 row_mirror row_mask:0xf bank_mask:0xf bound_ctrl:1
	s_nop 1
	v_max_f32_dpp v107, v107, v107 row_bcast:15 row_mask:0xa bank_mask:0xf
	s_nop 1
	v_max_f32_dpp v107, v107, v107 row_bcast:31 row_mask:0xc bank_mask:0xf
	s_nop 1
	v_readlane_b32 s32, v107, 63
	s_nop 3
	v_mov_b32_e32 v107, s32
	v_sub_f32_e32 v106, v106, v107
	v_mul_f32_e32 v106, 0x3fb8aa3b, v106
	v_sub_f32_e32 v103, v103, v107
	v_exp_f32_e32 v106, v106
	v_mul_f32_e32 v103, 0x3fb8aa3b, v103
	v_sub_f32_e32 v105, v105, v107
	v_exp_f32_e32 v103, v103
	v_mul_f32_e32 v105, 0x3fb8aa3b, v105
	v_sub_f32_e32 v104, v104, v107
	v_exp_f32_e32 v105, v105
	v_mul_f32_e32 v104, 0x3fb8aa3b, v104
	v_exp_f32_e32 v104, v104
	v_cndmask_b32_e64 v106, 0, v106, s[18:19]
	v_add_f32_e32 v108, 0, v106
	v_cndmask_b32_e64 v103, 0, v103, s[20:21]
	v_add_f32_e32 v108, v103, v108
	v_cndmask_b32_e64 v105, 0, v105, s[22:23]
	v_add_f32_e32 v108, v105, v108
	v_cndmask_b32_e64 v104, 0, v104, s[24:25]
	v_add_f32_e32 v107, v104, v108
	s_waitcnt lgkmcnt(0)
	s_nop 1
	v_add_f32_dpp v107, v107, v107 quad_perm:[1,0,3,2] row_mask:0xf bank_mask:0xf bound_ctrl:1
	s_nop 1
	v_add_f32_dpp v107, v107, v107 quad_perm:[2,3,0,1] row_mask:0xf bank_mask:0xf bound_ctrl:1
	s_nop 1
	v_add_f32_dpp v107, v107, v107 row_half_mirror row_mask:0xf bank_mask:0xf bound_ctrl:1
	s_nop 1
	v_add_f32_dpp v107, v107, v107 row_mirror row_mask:0xf bank_mask:0xf bound_ctrl:1
	s_nop 1
	v_add_f32_dpp v107, v107, v107 row_bcast:15 row_mask:0xa bank_mask:0xf
	s_nop 1
	v_add_f32_dpp v107, v107, v107 row_bcast:31 row_mask:0xc bank_mask:0xf
	s_nop 1
	v_readlane_b32 s32, v107, 63
	s_nop 3
	v_mov_b32_e32 v107, s32
	v_div_scale_f32 v108, s[0:1], v107, v107, 1.0
	v_rcp_f32_e32 v109, v108
	s_nop 0
	v_fma_f32 v110, -v108, v109, 1.0
	v_fmac_f32_e32 v109, v110, v109
	v_div_scale_f32 v110, vcc, 1.0, v107, 1.0
	v_mul_f32_e32 v111, v110, v109
	v_fma_f32 v112, -v108, v111, v110
	v_fmac_f32_e32 v111, v112, v109
	v_fma_f32 v108, -v108, v111, v110
	v_div_fmas_f32 v108, v108, v109, v111
	v_div_fixup_f32 v107, v108, v107, 1.0
	v_mul_f32_e32 v103, v103, v107
	v_cvt_pk_bf16_f32 v103, v103, s0
	ds_write_b16 v102, v103 offset:5760
	v_mul_f32_e32 v103, v105, v107
	v_cvt_pk_bf16_f32 v103, v103, s0
	v_mul_f32_e32 v106, v106, v107
	ds_write_b16 v102, v103 offset:5888
	v_mul_f32_e32 v103, v104, v107
	v_cvt_pk_bf16_f32 v106, v106, s0
	v_cvt_pk_bf16_f32 v103, v103, s0
	ds_write_b16 v102, v106 offset:5632
	ds_write_b16 v102, v103 offset:6016
	v_mov_b32_e32 v103, 0xff61b1e6
	v_mov_b32_e32 v106, 0xff61b1e6
	s_and_saveexec_b64 s[0:1], s[18:19]
	ds_read_b32 v106, v98 offset:1032
	s_or_b64 exec, exec, s[0:1]
	s_and_saveexec_b64 s[0:1], s[20:21]
	ds_read_b32 v103, v99 offset:1032
	s_or_b64 exec, exec, s[0:1]
	v_mov_b32_e32 v104, 0xff61b1e6
	v_mov_b32_e32 v105, 0xff61b1e6
	s_and_saveexec_b64 s[0:1], s[22:23]
	ds_read_b32 v105, v100 offset:1032
	s_or_b64 exec, exec, s[0:1]
	s_and_saveexec_b64 s[0:1], s[24:25]
	ds_read_b32 v104, v101 offset:1032
	s_or_b64 exec, exec, s[0:1]
	s_waitcnt lgkmcnt(0)
	v_max_f32_e32 v107, v104, v104
	v_max_f32_e32 v108, v105, v105
	v_max_f32_e32 v107, v108, v107
	v_max3_f32 v107, v106, v103, v107
	s_waitcnt lgkmcnt(0)
	s_nop 1
	v_max_f32_dpp v107, v107, v107 quad_perm:[1,0,3,2] row_mask:0xf bank_mask:0xf bound_ctrl:1
	s_nop 1
	v_max_f32_dpp v107, v107, v107 quad_perm:[2,3,0,1] row_mask:0xf bank_mask:0xf bound_ctrl:1
	s_nop 1
	v_max_f32_dpp v107, v107, v107 row_half_mirror row_mask:0xf bank_mask:0xf bound_ctrl:1
	s_nop 1
	v_max_f32_dpp v107, v107, v107 row_mirror row_mask:0xf bank_mask:0xf bound_ctrl:1
	s_nop 1
	v_max_f32_dpp v107, v107, v107 row_bcast:15 row_mask:0xa bank_mask:0xf
	s_nop 1
	v_max_f32_dpp v107, v107, v107 row_bcast:31 row_mask:0xc bank_mask:0xf
	s_nop 1
	v_readlane_b32 s32, v107, 63
	s_nop 3
	v_mov_b32_e32 v107, s32
	v_sub_f32_e32 v106, v106, v107
	v_mul_f32_e32 v106, 0x3fb8aa3b, v106
	v_sub_f32_e32 v103, v103, v107
	v_exp_f32_e32 v106, v106
	v_mul_f32_e32 v103, 0x3fb8aa3b, v103
	v_sub_f32_e32 v105, v105, v107
	v_exp_f32_e32 v103, v103
	v_mul_f32_e32 v105, 0x3fb8aa3b, v105
	v_sub_f32_e32 v104, v104, v107
	v_exp_f32_e32 v105, v105
	v_mul_f32_e32 v104, 0x3fb8aa3b, v104
	v_exp_f32_e32 v104, v104
	v_cndmask_b32_e64 v106, 0, v106, s[18:19]
	v_add_f32_e32 v108, 0, v106
	v_cndmask_b32_e64 v103, 0, v103, s[20:21]
	v_add_f32_e32 v108, v103, v108
	v_cndmask_b32_e64 v105, 0, v105, s[22:23]
	v_add_f32_e32 v108, v105, v108
	v_cndmask_b32_e64 v104, 0, v104, s[24:25]
	v_add_f32_e32 v107, v104, v108
	s_waitcnt lgkmcnt(0)
	s_nop 1
	v_add_f32_dpp v107, v107, v107 quad_perm:[1,0,3,2] row_mask:0xf bank_mask:0xf bound_ctrl:1
	s_nop 1
	v_add_f32_dpp v107, v107, v107 quad_perm:[2,3,0,1] row_mask:0xf bank_mask:0xf bound_ctrl:1
	s_nop 1
	v_add_f32_dpp v107, v107, v107 row_half_mirror row_mask:0xf bank_mask:0xf bound_ctrl:1
	s_nop 1
	v_add_f32_dpp v107, v107, v107 row_mirror row_mask:0xf bank_mask:0xf bound_ctrl:1
	s_nop 1
	v_add_f32_dpp v107, v107, v107 row_bcast:15 row_mask:0xa bank_mask:0xf
	s_nop 1
	v_add_f32_dpp v107, v107, v107 row_bcast:31 row_mask:0xc bank_mask:0xf
	s_nop 1
	v_readlane_b32 s32, v107, 63
	s_nop 3
	v_mov_b32_e32 v107, s32
	v_div_scale_f32 v108, s[0:1], v107, v107, 1.0
	v_rcp_f32_e32 v109, v108
	s_nop 0
	v_fma_f32 v110, -v108, v109, 1.0
	v_fmac_f32_e32 v109, v110, v109
	v_div_scale_f32 v110, vcc, 1.0, v107, 1.0
	v_mul_f32_e32 v111, v110, v109
	v_fma_f32 v112, -v108, v111, v110
	v_fmac_f32_e32 v111, v112, v109
	v_fma_f32 v108, -v108, v111, v110
	v_div_fmas_f32 v108, v108, v109, v111
	v_div_fixup_f32 v107, v108, v107, 1.0
	v_mul_f32_e32 v103, v103, v107
	v_cvt_pk_bf16_f32 v103, v103, s0
	ds_write_b16 v102, v103 offset:6272
	v_mul_f32_e32 v103, v105, v107
	v_cvt_pk_bf16_f32 v103, v103, s0
	ds_write_b16 v102, v103 offset:6400
	v_mul_f32_e32 v103, v104, v107
	v_mul_f32_e32 v106, v106, v107
	v_cvt_pk_bf16_f32 v103, v103, s0
	v_cvt_pk_bf16_f32 v106, v106, s0
	ds_write_b16 v102, v103 offset:6528
	v_mov_b32_e32 v103, 0xff61b1e6
	v_mov_b32_e32 v104, 0xff61b1e6
	ds_write_b16 v102, v106 offset:6144
	s_and_saveexec_b64 s[0:1], s[18:19]
	ds_read_b32 v104, v98 offset:1036
	s_or_b64 exec, exec, s[0:1]
	s_and_saveexec_b64 s[0:1], s[20:21]
	ds_read_b32 v103, v99 offset:1036
	s_or_b64 exec, exec, s[0:1]
	v_mov_b32_e32 v98, 0xff61b1e6
	v_mov_b32_e32 v99, 0xff61b1e6
	s_and_saveexec_b64 s[0:1], s[22:23]
	ds_read_b32 v99, v100 offset:1036
	s_or_b64 exec, exec, s[0:1]
	s_and_saveexec_b64 s[0:1], s[24:25]
	ds_read_b32 v98, v101 offset:1036
	s_or_b64 exec, exec, s[0:1]
	s_waitcnt lgkmcnt(0)
	v_max_f32_e32 v100, v98, v98
	v_max_f32_e32 v101, v99, v99
	v_max_f32_e32 v100, v101, v100
	v_max3_f32 v100, v104, v103, v100
	s_waitcnt lgkmcnt(0)
	s_nop 1
	v_max_f32_dpp v100, v100, v100 quad_perm:[1,0,3,2] row_mask:0xf bank_mask:0xf bound_ctrl:1
	s_nop 1
	v_max_f32_dpp v100, v100, v100 quad_perm:[2,3,0,1] row_mask:0xf bank_mask:0xf bound_ctrl:1
	s_nop 1
	v_max_f32_dpp v100, v100, v100 row_half_mirror row_mask:0xf bank_mask:0xf bound_ctrl:1
	s_nop 1
	v_max_f32_dpp v100, v100, v100 row_mirror row_mask:0xf bank_mask:0xf bound_ctrl:1
	s_nop 1
	v_max_f32_dpp v100, v100, v100 row_bcast:15 row_mask:0xa bank_mask:0xf
	s_nop 1
	v_max_f32_dpp v100, v100, v100 row_bcast:31 row_mask:0xc bank_mask:0xf
	s_nop 1
	v_readlane_b32 s32, v100, 63
	s_nop 3
	v_mov_b32_e32 v100, s32
	v_sub_f32_e32 v101, v104, v100
	v_sub_f32_e32 v103, v103, v100
	v_sub_f32_e32 v99, v99, v100
	v_sub_f32_e32 v98, v98, v100
	v_mul_f32_e32 v100, 0x3fb8aa3b, v101
	v_mul_f32_e32 v101, 0x3fb8aa3b, v103
	v_exp_f32_e32 v100, v100
	v_mul_f32_e32 v99, 0x3fb8aa3b, v99
	v_exp_f32_e32 v101, v101
	v_mul_f32_e32 v98, 0x3fb8aa3b, v98
	v_exp_f32_e32 v99, v99
	v_exp_f32_e32 v98, v98
	v_cndmask_b32_e64 v100, 0, v100, s[18:19]
	v_cndmask_b32_e64 v101, 0, v101, s[20:21]
	v_add_f32_e32 v103, 0, v100
	v_cndmask_b32_e64 v99, 0, v99, s[22:23]
	v_add_f32_e32 v103, v101, v103
	v_cndmask_b32_e64 v98, 0, v98, s[24:25]
	v_add_f32_e32 v103, v99, v103
	v_add_f32_e32 v103, v98, v103
	s_waitcnt lgkmcnt(0)
	s_nop 1
	v_add_f32_dpp v103, v103, v103 quad_perm:[1,0,3,2] row_mask:0xf bank_mask:0xf bound_ctrl:1
	s_nop 1
	v_add_f32_dpp v103, v103, v103 quad_perm:[2,3,0,1] row_mask:0xf bank_mask:0xf bound_ctrl:1
	s_nop 1
	v_add_f32_dpp v103, v103, v103 row_half_mirror row_mask:0xf bank_mask:0xf bound_ctrl:1
	s_nop 1
	v_add_f32_dpp v103, v103, v103 row_mirror row_mask:0xf bank_mask:0xf bound_ctrl:1
	s_nop 1
	v_add_f32_dpp v103, v103, v103 row_bcast:15 row_mask:0xa bank_mask:0xf
	s_nop 1
	v_add_f32_dpp v103, v103, v103 row_bcast:31 row_mask:0xc bank_mask:0xf
	s_nop 1
	v_readlane_b32 s32, v103, 63
	s_nop 3
	v_mov_b32_e32 v103, s32
	v_div_scale_f32 v104, s[0:1], v103, v103, 1.0
	v_rcp_f32_e32 v105, v104
	v_div_scale_f32 v106, vcc, 1.0, v103, 1.0
	v_fma_f32 v107, -v104, v105, 1.0
	v_fmac_f32_e32 v105, v107, v105
	v_mul_f32_e32 v107, v106, v105
	v_fma_f32 v108, -v104, v107, v106
	v_fmac_f32_e32 v107, v108, v105
	v_fma_f32 v104, -v104, v107, v106
	v_div_fmas_f32 v104, v104, v105, v107
	v_div_fixup_f32 v103, v104, v103, 1.0
	v_mul_f32_e32 v100, v100, v103
	v_mul_f32_e32 v101, v101, v103
	v_mul_f32_e32 v99, v99, v103
	v_mul_f32_e32 v98, v98, v103
	v_cvt_pk_bf16_f32 v100, v100, s0
	v_cvt_pk_bf16_f32 v101, v101, s0
	v_cvt_pk_bf16_f32 v99, v99, s0
	v_cvt_pk_bf16_f32 v98, v98, s0
	ds_write_b16 v102, v100 offset:6656
	ds_write_b16 v102, v101 offset:6784
	ds_write_b16 v102, v99 offset:6912
	ds_write_b16 v102, v98 offset:7040
	s_waitcnt vmcnt(7)
	ds_write_b128 v143, v[10:13] offset:7168
	s_waitcnt vmcnt(6)
	ds_write_b128 v143, v[18:21] offset:8448
	s_waitcnt vmcnt(5)
	ds_write_b128 v143, v[30:33] offset:9728
	s_waitcnt vmcnt(4)
	ds_write_b128 v143, v[38:41] offset:11008
	s_waitcnt vmcnt(3)
	ds_write_b128 v143, v[50:53] offset:12288
	s_waitcnt vmcnt(2)
	ds_write_b128 v143, v[54:57] offset:13568
	s_waitcnt vmcnt(1)
	ds_write_b128 v143, v[58:61] offset:14848
	s_waitcnt vmcnt(0)
	ds_write_b128 v143, v[62:65] offset:16128
	s_and_b64 vcc, exec, s[26:27]
	s_cbranch_vccz .LBB0_2629
	ds_read2_b32 v[10:11], v142 offset0:96 offset1:100
	ds_read2_b32 v[30:31], v142 offset0:104 offset1:108
	s_waitcnt lgkmcnt(1)
	v_add_u32_e32 v10, s48, v10
	v_add_u32_e32 v12, s48, v11
	s_waitcnt lgkmcnt(0)
	v_add_u32_e32 v32, s48, v30
	v_add_u32_e32 v30, s48, v31
	v_ashrrev_i32_e32 v11, 31, v10
	v_ashrrev_i32_e32 v13, 31, v12
	v_ashrrev_i32_e32 v33, 31, v32
	v_ashrrev_i32_e32 v31, 31, v30
	v_lshlrev_b64 v[10:11], 9, v[10:11]
	v_lshlrev_b64 v[12:13], 9, v[12:13]
	v_lshlrev_b64 v[32:33], 9, v[32:33]
	v_lshlrev_b64 v[30:31], 9, v[30:31]
	v_lshl_add_u64 v[10:11], v[130:131], 0, v[10:11]
	v_lshl_add_u64 v[18:19], v[130:131], 0, v[12:13]
	v_lshl_add_u64 v[32:33], v[130:131], 0, v[32:33]
	v_lshl_add_u64 v[38:39], v[130:131], 0, v[30:31]
	global_load_dwordx4 v[10:13], v[10:11], off
	s_nop 0
	global_load_dwordx4 v[18:21], v[18:19], off
	ds_read2_b32 v[50:51], v142 offset0:112 offset1:116
	global_load_dwordx4 v[30:33], v[32:33], off
	s_nop 0
	global_load_dwordx4 v[38:41], v[38:39], off
	ds_read2_b32 v[58:59], v142 offset0:120 offset1:124
	s_waitcnt lgkmcnt(1)
	v_add_u32_e32 v52, s48, v50
	v_add_u32_e32 v50, s48, v51
	s_waitcnt lgkmcnt(0)
	v_add_u32_e32 v60, s48, v58
	v_add_u32_e32 v58, s48, v59
	v_ashrrev_i32_e32 v53, 31, v52
	v_ashrrev_i32_e32 v51, 31, v50
	v_ashrrev_i32_e32 v61, 31, v60
	v_ashrrev_i32_e32 v59, 31, v58
	v_lshlrev_b64 v[52:53], 9, v[52:53]
	v_lshlrev_b64 v[50:51], 9, v[50:51]
	v_lshlrev_b64 v[60:61], 9, v[60:61]
	v_lshlrev_b64 v[58:59], 9, v[58:59]
	v_lshl_add_u64 v[52:53], v[130:131], 0, v[52:53]
	v_lshl_add_u64 v[54:55], v[130:131], 0, v[50:51]
	v_lshl_add_u64 v[60:61], v[130:131], 0, v[60:61]
	v_lshl_add_u64 v[62:63], v[130:131], 0, v[58:59]
	global_load_dwordx4 v[50:53], v[52:53], off
	s_nop 0
	global_load_dwordx4 v[54:57], v[54:55], off
	s_nop 0
	global_load_dwordx4 v[58:61], v[60:61], off
	s_nop 0
	global_load_dwordx4 v[62:65], v[62:63], off
